# LN1/LN2 output stores back to default cache policy (nt kept on the streaming row loads only); P0 idx-k cache conversion in one shot
# baseline (speedup 1.0000x reference)
.Lln1_addr:
	s_and_saveexec_b64 s[8:9], s[4:5]
	global_load_dwordx2 v[132:133], v[144:145], off
	global_load_dwordx2 v[134:135], v[146:147], off
	s_mov_b64 exec, s[8:9]
	s_waitcnt vmcnt(18)
	v_sub_f32_e32 v101, v101, v46
	v_sub_f32_e32 v100, v100, v46
	v_sub_f32_e32 v103, v103, v46
	v_sub_f32_e32 v102, v102, v46
	v_pk_mul_f32 v[100:101], v[100:101], v[44:45] op_sel_hi:[1,0]
	v_pk_mul_f32 v[102:103], v[102:103], v[44:45] op_sel_hi:[1,0]
	v_pk_fma_f32 v[100:101], v[100:101], v[60:61], v[76:77]
	v_pk_fma_f32 v[102:103], v[102:103], v[62:63], v[78:79]
	v_cvt_pk_bf16_f32 v100, v100, v101
	v_cvt_pk_bf16_f32 v101, v102, v103
	global_store_dwordx2 v[140:141], v[100:101], off
	global_load_dwordx4 v[100:103], v[136:137], off nt
	s_waitcnt vmcnt(18)
	v_sub_f32_e32 v105, v105, v46
	v_sub_f32_e32 v104, v104, v46
	v_sub_f32_e32 v107, v107, v46
	v_sub_f32_e32 v106, v106, v46
	v_pk_mul_f32 v[104:105], v[104:105], v[44:45] op_sel_hi:[1,0]
	v_pk_mul_f32 v[106:107], v[106:107], v[44:45] op_sel_hi:[1,0]
	v_pk_fma_f32 v[104:105], v[104:105], v[64:65], v[80:81]
	v_pk_fma_f32 v[106:107], v[106:107], v[66:67], v[82:83]
	v_cvt_pk_bf16_f32 v104, v104, v105
	v_cvt_pk_bf16_f32 v105, v106, v107
	global_store_dwordx2 v[140:141], v[104:105], off offset:512
	global_load_dwordx4 v[104:107], v[136:137], off offset:1024 nt
	s_waitcnt vmcnt(18)
	v_sub_f32_e32 v109, v109, v46
	v_sub_f32_e32 v108, v108, v46
	v_sub_f32_e32 v111, v111, v46
	v_sub_f32_e32 v110, v110, v46
	v_pk_mul_f32 v[108:109], v[108:109], v[44:45] op_sel_hi:[1,0]
	v_pk_mul_f32 v[110:111], v[110:111], v[44:45] op_sel_hi:[1,0]
	v_pk_fma_f32 v[108:109], v[108:109], v[68:69], v[84:85]
	v_pk_fma_f32 v[110:111], v[110:111], v[70:71], v[86:87]
	v_cvt_pk_bf16_f32 v108, v108, v109
	v_cvt_pk_bf16_f32 v109, v110, v111
	global_store_dwordx2 v[140:141], v[108:109], off offset:1024
	global_load_dwordx4 v[108:111], v[136:137], off offset:2048 nt
	s_waitcnt vmcnt(18)
	v_sub_f32_e32 v113, v113, v46
	v_sub_f32_e32 v112, v112, v46
	v_sub_f32_e32 v115, v115, v46
	v_sub_f32_e32 v114, v114, v46
	v_pk_mul_f32 v[112:113], v[112:113], v[44:45] op_sel_hi:[1,0]
	v_pk_mul_f32 v[114:115], v[114:115], v[44:45] op_sel_hi:[1,0]
	v_pk_fma_f32 v[112:113], v[112:113], v[72:73], v[88:89]
	v_pk_fma_f32 v[114:115], v[114:115], v[74:75], v[90:91]
	v_cvt_pk_bf16_f32 v112, v112, v113
	v_cvt_pk_bf16_f32 v113, v114, v115
	global_store_dwordx2 v[140:141], v[112:113], off offset:1536
	global_load_dwordx4 v[112:115], v[136:137], off offset:3072 nt
	s_waitcnt vmcnt(18)
	v_sub_f32_e32 v117, v117, v16
	v_sub_f32_e32 v116, v116, v16
	v_sub_f32_e32 v119, v119, v16
	v_sub_f32_e32 v118, v118, v16
	v_pk_mul_f32 v[116:117], v[116:117], v[18:19] op_sel_hi:[1,0]
	v_pk_mul_f32 v[118:119], v[118:119], v[18:19] op_sel_hi:[1,0]
	v_pk_fma_f32 v[116:117], v[116:117], v[60:61], v[76:77]
	v_pk_fma_f32 v[118:119], v[118:119], v[62:63], v[78:79]
	v_cvt_pk_bf16_f32 v116, v116, v117
	v_cvt_pk_bf16_f32 v117, v118, v119
	global_store_dwordx2 v[142:143], v[116:117], off
	global_load_dwordx4 v[116:119], v[138:139], off nt
	s_waitcnt vmcnt(18)
	v_sub_f32_e32 v121, v121, v16
	v_sub_f32_e32 v120, v120, v16
	v_sub_f32_e32 v123, v123, v16
	v_sub_f32_e32 v122, v122, v16
	v_pk_mul_f32 v[120:121], v[120:121], v[18:19] op_sel_hi:[1,0]
	v_pk_mul_f32 v[122:123], v[122:123], v[18:19] op_sel_hi:[1,0]
	v_pk_fma_f32 v[120:121], v[120:121], v[64:65], v[80:81]
	v_pk_fma_f32 v[122:123], v[122:123], v[66:67], v[82:83]
	v_cvt_pk_bf16_f32 v120, v120, v121
	v_cvt_pk_bf16_f32 v121, v122, v123
	global_store_dwordx2 v[142:143], v[120:121], off offset:512
	global_load_dwordx4 v[120:123], v[138:139], off offset:1024 nt
	s_waitcnt vmcnt(18)
	v_sub_f32_e32 v125, v125, v16
	v_sub_f32_e32 v124, v124, v16
	v_sub_f32_e32 v127, v127, v16
	v_sub_f32_e32 v126, v126, v16
	v_pk_mul_f32 v[124:125], v[124:125], v[18:19] op_sel_hi:[1,0]
	v_pk_mul_f32 v[126:127], v[126:127], v[18:19] op_sel_hi:[1,0]
	v_pk_fma_f32 v[124:125], v[124:125], v[68:69], v[84:85]
	v_pk_fma_f32 v[126:127], v[126:127], v[70:71], v[86:87]
	v_cvt_pk_bf16_f32 v124, v124, v125
	v_cvt_pk_bf16_f32 v125, v126, v127
	global_store_dwordx2 v[142:143], v[124:125], off offset:1024
	global_load_dwordx4 v[124:127], v[138:139], off offset:2048 nt
	s_waitcnt vmcnt(18)
	v_sub_f32_e32 v129, v129, v16
	v_sub_f32_e32 v128, v128, v16
	v_sub_f32_e32 v131, v131, v16
	v_sub_f32_e32 v130, v130, v16
	v_pk_mul_f32 v[128:129], v[128:129], v[18:19] op_sel_hi:[1,0]
	v_pk_mul_f32 v[130:131], v[130:131], v[18:19] op_sel_hi:[1,0]
	v_pk_fma_f32 v[128:129], v[128:129], v[72:73], v[88:89]
	v_pk_fma_f32 v[130:131], v[130:131], v[74:75], v[90:91]
	v_cvt_pk_bf16_f32 v128, v128, v129
	v_cvt_pk_bf16_f32 v129, v130, v131
	global_store_dwordx2 v[142:143], v[128:129], off offset:1536
	global_load_dwordx4 v[128:131], v[138:139], off offset:3072 nt
	s_and_b64 vcc, exec, s[26:27]
	s_cbranch_vccnz .Lln1_loop
	s_waitcnt vmcnt(0)

.Lln2_addr:
	s_and_saveexec_b64 s[8:9], s[0:1]
	global_load_dwordx2 v[170:171], v[178:179], off
	global_load_dwordx2 v[172:173], v[180:181], off
	s_mov_b64 exec, s[8:9]
	s_waitcnt vmcnt(16)
	v_lshlrev_b32_e32 v186, 16, v100
	v_and_b32_e32 v187, 0xffff0000, v100
	v_lshlrev_b32_e32 v188, 16, v101
	v_and_b32_e32 v189, 0xffff0000, v101
	v_sub_f32_e32 v186, v186, v41
	v_sub_f32_e32 v187, v187, v41
	v_sub_f32_e32 v188, v188, v41
	v_sub_f32_e32 v189, v189, v41
	v_pk_mul_f32 v[186:187], v[186:187], v[14:15] op_sel_hi:[1,0]
	v_pk_mul_f32 v[188:189], v[188:189], v[14:15] op_sel_hi:[1,0]
	v_pk_fma_f32 v[120:121], v[60:61], v[186:187], v[76:77]
	v_pk_fma_f32 v[122:123], v[62:63], v[188:189], v[78:79]
	global_store_dwordx4 v[182:183], v[120:123], off
	global_load_dwordx2 v[100:101], v[174:175], off nt
	s_waitcnt vmcnt(16)
	v_lshlrev_b32_e32 v186, 16, v102
	v_and_b32_e32 v187, 0xffff0000, v102
	v_lshlrev_b32_e32 v188, 16, v103
	v_and_b32_e32 v189, 0xffff0000, v103
	v_sub_f32_e32 v186, v186, v41
	v_sub_f32_e32 v187, v187, v41
	v_sub_f32_e32 v188, v188, v41
	v_sub_f32_e32 v189, v189, v41
	v_pk_mul_f32 v[186:187], v[186:187], v[14:15] op_sel_hi:[1,0]
	v_pk_mul_f32 v[188:189], v[188:189], v[14:15] op_sel_hi:[1,0]
	v_pk_fma_f32 v[124:125], v[64:65], v[186:187], v[80:81]
	v_pk_fma_f32 v[126:127], v[66:67], v[188:189], v[82:83]
	global_store_dwordx4 v[182:183], v[124:127], off offset:1024
	global_load_dwordx2 v[102:103], v[174:175], off offset:512 nt
	s_waitcnt vmcnt(16)
	v_lshlrev_b32_e32 v186, 16, v104
	v_and_b32_e32 v187, 0xffff0000, v104
	v_lshlrev_b32_e32 v188, 16, v105
	v_and_b32_e32 v189, 0xffff0000, v105
	v_sub_f32_e32 v186, v186, v41
	v_sub_f32_e32 v187, v187, v41
	v_sub_f32_e32 v188, v188, v41
	v_sub_f32_e32 v189, v189, v41
	v_pk_mul_f32 v[186:187], v[186:187], v[14:15] op_sel_hi:[1,0]
	v_pk_mul_f32 v[188:189], v[188:189], v[14:15] op_sel_hi:[1,0]
	v_pk_fma_f32 v[128:129], v[68:69], v[186:187], v[84:85]
	v_pk_fma_f32 v[130:131], v[70:71], v[188:189], v[86:87]
	global_store_dwordx4 v[182:183], v[128:131], off offset:2048
	global_load_dwordx2 v[104:105], v[174:175], off offset:1024 nt
	s_waitcnt vmcnt(16)
	v_lshlrev_b32_e32 v186, 16, v106
	v_and_b32_e32 v187, 0xffff0000, v106
	v_lshlrev_b32_e32 v188, 16, v107
	v_and_b32_e32 v189, 0xffff0000, v107
	v_sub_f32_e32 v186, v186, v41
	v_sub_f32_e32 v187, v187, v41
	v_sub_f32_e32 v188, v188, v41
	v_sub_f32_e32 v189, v189, v41
	v_pk_mul_f32 v[186:187], v[186:187], v[14:15] op_sel_hi:[1,0]
	v_pk_mul_f32 v[188:189], v[188:189], v[14:15] op_sel_hi:[1,0]
	v_pk_fma_f32 v[132:133], v[72:73], v[186:187], v[88:89]
	v_pk_fma_f32 v[134:135], v[74:75], v[188:189], v[90:91]
	global_store_dwordx4 v[182:183], v[132:135], off offset:3072
	global_load_dwordx2 v[106:107], v[174:175], off offset:1536 nt
	s_waitcnt vmcnt(16)
	v_lshlrev_b32_e32 v186, 16, v108
	v_and_b32_e32 v187, 0xffff0000, v108
	v_lshlrev_b32_e32 v188, 16, v109
	v_and_b32_e32 v189, 0xffff0000, v109
	v_sub_f32_e32 v186, v186, v161
	v_sub_f32_e32 v187, v187, v161
	v_sub_f32_e32 v188, v188, v161
	v_sub_f32_e32 v189, v189, v161
	v_pk_mul_f32 v[186:187], v[186:187], v[154:155] op_sel_hi:[1,0]
	v_pk_mul_f32 v[188:189], v[188:189], v[154:155] op_sel_hi:[1,0]
	v_pk_fma_f32 v[136:137], v[60:61], v[186:187], v[76:77]
	v_pk_fma_f32 v[138:139], v[62:63], v[188:189], v[78:79]
	global_store_dwordx4 v[184:185], v[136:139], off
	global_load_dwordx2 v[108:109], v[176:177], off nt
	s_waitcnt vmcnt(16)
	v_lshlrev_b32_e32 v186, 16, v110
	v_and_b32_e32 v187, 0xffff0000, v110
	v_lshlrev_b32_e32 v188, 16, v111
	v_and_b32_e32 v189, 0xffff0000, v111
	v_sub_f32_e32 v186, v186, v161
	v_sub_f32_e32 v187, v187, v161
	v_sub_f32_e32 v188, v188, v161
	v_sub_f32_e32 v189, v189, v161
	v_pk_mul_f32 v[186:187], v[186:187], v[154:155] op_sel_hi:[1,0]
	v_pk_mul_f32 v[188:189], v[188:189], v[154:155] op_sel_hi:[1,0]
	v_pk_fma_f32 v[140:141], v[64:65], v[186:187], v[80:81]
	v_pk_fma_f32 v[142:143], v[66:67], v[188:189], v[82:83]
	global_store_dwordx4 v[184:185], v[140:143], off offset:1024
	global_load_dwordx2 v[110:111], v[176:177], off offset:512 nt
	s_waitcnt vmcnt(16)
	v_lshlrev_b32_e32 v186, 16, v112
	v_and_b32_e32 v187, 0xffff0000, v112
	v_lshlrev_b32_e32 v188, 16, v113
	v_and_b32_e32 v189, 0xffff0000, v113
	v_sub_f32_e32 v186, v186, v161
	v_sub_f32_e32 v187, v187, v161
	v_sub_f32_e32 v188, v188, v161
	v_sub_f32_e32 v189, v189, v161
	v_pk_mul_f32 v[186:187], v[186:187], v[154:155] op_sel_hi:[1,0]
	v_pk_mul_f32 v[188:189], v[188:189], v[154:155] op_sel_hi:[1,0]
	v_pk_fma_f32 v[144:145], v[68:69], v[186:187], v[84:85]
	v_pk_fma_f32 v[146:147], v[70:71], v[188:189], v[86:87]
	global_store_dwordx4 v[184:185], v[144:147], off offset:2048
	global_load_dwordx2 v[112:113], v[176:177], off offset:1024 nt
	s_waitcnt vmcnt(16)
	v_lshlrev_b32_e32 v186, 16, v114
	v_and_b32_e32 v187, 0xffff0000, v114
	v_lshlrev_b32_e32 v188, 16, v115
	v_and_b32_e32 v189, 0xffff0000, v115
	v_sub_f32_e32 v186, v186, v161
	v_sub_f32_e32 v187, v187, v161
	v_sub_f32_e32 v188, v188, v161
	v_sub_f32_e32 v189, v189, v161
	v_pk_mul_f32 v[186:187], v[186:187], v[154:155] op_sel_hi:[1,0]
	v_pk_mul_f32 v[188:189], v[188:189], v[154:155] op_sel_hi:[1,0]
	v_pk_fma_f32 v[148:149], v[72:73], v[186:187], v[88:89]
	v_pk_fma_f32 v[150:151], v[74:75], v[188:189], v[90:91]
	global_store_dwordx4 v[184:185], v[148:151], off offset:3072
	global_load_dwordx2 v[114:115], v[176:177], off offset:1536 nt
	s_and_b64 vcc, exec, s[20:21]
	s_cbranch_vccnz .Lln2_loop
	s_waitcnt vmcnt(0)
